# v26 plus attention epilogue row-sum merge via v_permlane32_swap instead of two ds_bpermute LDS round trips (bit-identical sums)
# baseline (speedup 1.0000x reference)
; __device__ __forceinline__ unsigned cvtpk(float lo, float hi) { f32x2_t v = {lo, hi}; bf16x2_t b = __builtin_convertvector(v, bf16x2_t); return __builtin_bit_cast(unsigned, b); }
; __device__ __forceinline__ void attn_phase(LAS unsigned char* lds, const bf16_t* Qb, const bf16_t* Kimg, const bf16_t* Vimg, bf16_t* AB, int bid, int G, int wave_k) {
;     ...
;         int lane_o = lane; asm volatile("" : "+v"(lane_o));
; #pragma unroll
;         for (int b = 0; b < 2; ++b) { const float lt = lrun[b] + __shfl_xor(lrun[b], 32), il = 1.f / lt;
;             bf16_t* orow = AB + (size_t)(qrow0 + 32 * b + (lane_o & 31)) * DM + h * VH + 4 * (lane_o >> 5);
; #pragma unroll
;             for (int g = 0; g < 4; ++g) {
;                 *(u32x2*)(orow + 8 * g) = (u32x2){cvtpk(o[b][0][4 * g] * il, o[b][0][4 * g + 1] * il), cvtpk(o[b][0][4 * g + 2] * il, o[b][0][4 * g + 3] * il)};
;                 *(u32x2*)(orow + 32 + 8 * g) = (u32x2){cvtpk(o[b][1][4 * g] * il, o[b][1][4 * g + 1] * il), cvtpk(o[b][1][4 * g + 2] * il, o[b][1][4 * g + 3] * il)}; } }
.LBB0_947:
	s_waitcnt lgkmcnt(0)
	s_barrier
	v_and_b32_e32 v66, 64, v229
	v_xor_b32_e32 v64, 32, v229
	v_add_u32_e32 v66, 64, v66
	v_mov_b32_e32 v65, v235
	v_cmp_lt_i32_e32 vcc, v64, v66
	s_lshl_b32 s0, s59, 7
	s_add_u32 s0, s40, s0
	v_cndmask_b32_e32 v64, v229, v64, vcc
	v_lshlrev_b32_e32 v69, 2, v64
	v_and_or_b32 v64, v65, 31, s60
	v_ashrrev_i32_e32 v65, 3, v65
	v_and_b32_e32 v66, -4, v65
	v_mov_b32_e32 v65, v223
	v_mov_b32_e32 v72, v223
	s_addc_u32 s1, s41, 0
	v_ashrrev_i32_e32 v67, 31, v66
	v_lshl_add_u64 v[66:67], v[66:67], 1, s[0:1]
	s_add_i32 s26, s26, s27
	v_permlane32_swap_b32_e32 v65, v72
	v_add_f32_e32 v65, v65, v72
	v_div_scale_f32 v68, s[0:1], v65, v65, 1.0
	v_rcp_f32_e32 v70, v68
	s_cmpk_lt_i32 s26, 0x100
	v_fma_f32 v71, -v68, v70, 1.0
	v_fmac_f32_e32 v70, v71, v70
	v_div_scale_f32 v71, vcc, 1.0, v65, 1.0
	v_mul_f32_e32 v72, v71, v70
	v_fma_f32 v73, -v68, v72, v71
	v_fmac_f32_e32 v72, v73, v70
	v_fma_f32 v68, -v68, v72, v71
	v_div_fmas_f32 v68, v68, v70, v72
	v_div_fixup_f32 v68, v68, v65, 1.0
	v_ashrrev_i32_e32 v65, 31, v64
	v_lshlrev_b64 v[70:71], 11, v[64:65]
	v_pk_mul_f32 v[32:33], v[32:33], v[68:69] op_sel_hi:[1,0]
	v_pk_mul_f32 v[34:35], v[34:35], v[68:69] op_sel_hi:[1,0]
	v_lshl_add_u64 v[70:71], v[66:67], 0, v[70:71]
	v_cvt_pk_bf16_f32 v32, v32, v33
	v_cvt_pk_bf16_f32 v33, v34, v35
	global_store_dwordx2 v[70:71], v[32:33], off offset:64
	v_pk_mul_f32 v[32:33], v[52:53], v[68:69] op_sel_hi:[1,0]
	v_pk_mul_f32 v[34:35], v[54:55], v[68:69] op_sel_hi:[1,0]
	v_cvt_pk_bf16_f32 v32, v32, v33
	v_cvt_pk_bf16_f32 v33, v34, v35
	global_store_dwordx2 v[70:71], v[32:33], off offset:16
	v_pk_mul_f32 v[32:33], v[36:37], v[68:69] op_sel_hi:[1,0]
	v_pk_mul_f32 v[34:35], v[38:39], v[68:69] op_sel_hi:[1,0]
	v_cvt_pk_bf16_f32 v32, v32, v33
	v_cvt_pk_bf16_f32 v33, v34, v35
	global_store_dwordx2 v[70:71], v[32:33], off offset:80
	v_pk_mul_f32 v[32:33], v[56:57], v[68:69] op_sel_hi:[1,0]
	v_pk_mul_f32 v[34:35], v[58:59], v[68:69] op_sel_hi:[1,0]
	v_cvt_pk_bf16_f32 v32, v32, v33
	v_cvt_pk_bf16_f32 v33, v34, v35
	global_store_dwordx2 v[70:71], v[32:33], off offset:32
	v_pk_mul_f32 v[32:33], v[40:41], v[68:69] op_sel_hi:[1,0]
	v_pk_mul_f32 v[34:35], v[42:43], v[68:69] op_sel_hi:[1,0]
	v_cvt_pk_bf16_f32 v32, v32, v33
	v_cvt_pk_bf16_f32 v33, v34, v35
	global_store_dwordx2 v[70:71], v[32:33], off offset:96
	v_pk_mul_f32 v[32:33], v[60:61], v[68:69] op_sel_hi:[1,0]
	v_pk_mul_f32 v[34:35], v[62:63], v[68:69] op_sel_hi:[1,0]
	v_cvt_pk_bf16_f32 v32, v32, v33
	v_cvt_pk_bf16_f32 v33, v34, v35
	global_store_dwordx2 v[70:71], v[32:33], off offset:48
	v_pk_mul_f32 v[32:33], v[44:45], v[68:69] op_sel_hi:[1,0]
	v_pk_mul_f32 v[34:35], v[46:47], v[68:69] op_sel_hi:[1,0]
	v_cvt_pk_bf16_f32 v32, v32, v33
	v_cvt_pk_bf16_f32 v33, v34, v35
	global_store_dwordx2 v[70:71], v[32:33], off offset:112
	v_mov_b32_e32 v32, v222
	v_mov_b32_e32 v33, v222
	v_pk_mul_f32 v[48:49], v[48:49], v[68:69] op_sel_hi:[1,0]
	v_pk_mul_f32 v[50:51], v[50:51], v[68:69] op_sel_hi:[1,0]
	v_cvt_pk_bf16_f32 v48, v48, v49
	v_cvt_pk_bf16_f32 v49, v50, v51
	v_permlane32_swap_b32_e32 v32, v33
	v_add_f32_e32 v32, v32, v33
	v_div_scale_f32 v33, s[0:1], v32, v32, 1.0
	v_rcp_f32_e32 v34, v33
	global_store_dwordx2 v[70:71], v[48:49], off
	v_fma_f32 v35, -v33, v34, 1.0
	v_fmac_f32_e32 v34, v35, v34
	v_div_scale_f32 v35, vcc, 1.0, v32, 1.0
	v_mul_f32_e32 v36, v35, v34
	v_fma_f32 v37, -v33, v36, v35
	v_fmac_f32_e32 v36, v37, v34
	v_fma_f32 v33, -v33, v36, v35
	v_div_fmas_f32 v33, v33, v34, v36
	v_or_b32_e32 v34, 32, v64
	v_div_fixup_f32 v32, v33, v32, 1.0
	v_ashrrev_i32_e32 v35, 31, v34
	v_lshlrev_b64 v[34:35], 11, v[34:35]
	v_pk_mul_f32 v[0:1], v[0:1], v[32:33] op_sel_hi:[1,0]
	v_pk_mul_f32 v[2:3], v[2:3], v[32:33] op_sel_hi:[1,0]
	v_lshl_add_u64 v[34:35], v[66:67], 0, v[34:35]
	v_cvt_pk_bf16_f32 v0, v0, v1
	v_cvt_pk_bf16_f32 v1, v2, v3
	global_store_dwordx2 v[34:35], v[0:1], off offset:64
	v_pk_mul_f32 v[0:1], v[20:21], v[32:33] op_sel_hi:[1,0]
	v_pk_mul_f32 v[2:3], v[22:23], v[32:33] op_sel_hi:[1,0]
	v_cvt_pk_bf16_f32 v0, v0, v1
	v_cvt_pk_bf16_f32 v1, v2, v3
	global_store_dwordx2 v[34:35], v[0:1], off offset:16
	v_pk_mul_f32 v[0:1], v[4:5], v[32:33] op_sel_hi:[1,0]
	v_pk_mul_f32 v[2:3], v[6:7], v[32:33] op_sel_hi:[1,0]
	v_cvt_pk_bf16_f32 v0, v0, v1
	v_cvt_pk_bf16_f32 v1, v2, v3
	global_store_dwordx2 v[34:35], v[0:1], off offset:80
	v_pk_mul_f32 v[0:1], v[24:25], v[32:33] op_sel_hi:[1,0]
	v_pk_mul_f32 v[2:3], v[26:27], v[32:33] op_sel_hi:[1,0]
	v_cvt_pk_bf16_f32 v0, v0, v1
	v_cvt_pk_bf16_f32 v1, v2, v3
	global_store_dwordx2 v[34:35], v[0:1], off offset:32
	v_pk_mul_f32 v[0:1], v[8:9], v[32:33] op_sel_hi:[1,0]
	v_pk_mul_f32 v[2:3], v[10:11], v[32:33] op_sel_hi:[1,0]
	v_cvt_pk_bf16_f32 v0, v0, v1
	v_cvt_pk_bf16_f32 v1, v2, v3
	global_store_dwordx2 v[34:35], v[0:1], off offset:96
	v_pk_mul_f32 v[0:1], v[28:29], v[32:33] op_sel_hi:[1,0]
	v_pk_mul_f32 v[2:3], v[30:31], v[32:33] op_sel_hi:[1,0]
	v_cvt_pk_bf16_f32 v0, v0, v1
	v_cvt_pk_bf16_f32 v1, v2, v3
	v_pk_mul_f32 v[16:17], v[16:17], v[32:33] op_sel_hi:[1,0]
	v_pk_mul_f32 v[18:19], v[18:19], v[32:33] op_sel_hi:[1,0]
	global_store_dwordx2 v[34:35], v[0:1], off offset:48
	v_pk_mul_f32 v[0:1], v[12:13], v[32:33] op_sel_hi:[1,0]
	v_pk_mul_f32 v[2:3], v[14:15], v[32:33] op_sel_hi:[1,0]
	v_cvt_pk_bf16_f32 v16, v16, v17
	v_cvt_pk_bf16_f32 v17, v18, v19
	v_cvt_pk_bf16_f32 v0, v0, v1
	v_cvt_pk_bf16_f32 v1, v2, v3
	global_store_dwordx2 v[34:35], v[16:17], off
	global_store_dwordx2 v[34:35], v[0:1], off offset:112
	s_cbranch_scc0 .LBB0_985
